# GEMM phases: one static s_setprio 1 for waves 4-7 for the whole phase (cleared at the closing barrier); no per-segment toggles
# baseline (speedup 1.0000x reference)
; #define PG8_STAGE(bufoff, gbase, voff) do { _Pragma("unroll") for (int _i = 0; _i < 2; ++_i) \
;         __builtin_amdgcn_global_load_lds((const unsigned*)((const char*)(gbase) + (voff)[_i]), (PG8_LAS unsigned*)(lds + (bufoff) + ldsw + _i * 8192), 16, 0, 0); } while (0)
; #define PG8_WAIT_V(n) asm volatile("s_waitcnt vmcnt(" #n ")" ::: "memory")
; #define PG8_BAR __builtin_amdgcn_s_barrier()
; template <class Epi, class Sched>
; __device__ __forceinline__ void gemm_phase(PG8_LAS unsigned char* lds, const Gemm g, const Sched& S, const Epi& E) {
;     ...
;     for (int i = 0; i < 2; ++i) { int R, C; stage_rc(tid * 16 + i * 8192, R, C); const int Rb = Epi::PERM ? ((R & ~31) + perm32(R & 31)) : R;
;         voffA[i] = (unsigned)(R * K + C) * 2u; voffB[i] = (unsigned)(Rb * K + C) * 2u; }
;     const size_t kstep = (size_t)(BK * 2);
;     const size_t hstep = (size_t)HALF * K * 2;
;     const size_t tstep = 2 * hstep;
;     const unsigned ldsw = (unsigned)wid * 1024u;
;     const int aoff = lds_byte(wr * 64 + fr, fq * 8), boff = lds_byte(wc * 32 + fr, fq * 8);
;     ...
;     Unit cur, nxt; int ui = 0;
;     if (!S.next(0, cur)) return;
;     f32x4 acc[2][2][4][2];
; #pragma unroll
;     for (int a = 0; a < 2; ++a)
; #pragma unroll
;         for (int b = 0; b < 2; ++b)
; #pragma unroll
;             for (int m = 0; m < 4; ++m)
; #pragma unroll
;                 for (int n = 0; n < 2; ++n) acc[a][b][m][n] = (f32x4){0.f, 0.f, 0.f, 0.f};
;     bf16x8 At[4][2], B0[2][2], B1[2][2];
;     const char* cA = (const char*)g.A + (size_t)cur.pm * tstep; const char* cB = (const char*)g.Bt + (size_t)cur.pn * tstep;
;     S.a_ready(cur);
;     PG8_STAGE(PG8_SB(0, 0), cB, voffB); PG8_STAGE(PG8_SA(0, 0), cA, voffA); PG8_STAGE(PG8_SB(0, 1), cB + hstep, voffB); PG8_STAGE(PG8_SA(0, 1), cA + hstep, voffA);
;     if (wr == 1) PG8_BAR;
;     PG8_WAIT_V(4); PG8_BAR;
;     PG8_STAGE(PG8_SB(1, 0), cB + kstep, voffB); PG8_STAGE(PG8_SA(1, 0), cA + kstep, voffA); PG8_STAGE(PG8_SB(1, 1), cB + hstep + kstep, voffB);
.LBB0_159:
	s_or_b64 exec, exec, s[0:1]
	v_readfirstlane_b32 s98, v244
	s_nop 3
	s_lshr_b32 s98, s98, 6
	s_cmp_ge_u32 s98, 4
	s_cbranch_scc0 .Lgprio_0
	s_setprio 1
.Lgprio_0:
	s_add_u32 s44, s58, 0x3000000
	s_addc_u32 s45, s59, 0
	s_add_u32 s50, s58, 0x7000000
	s_addc_u32 s51, s59, 0
	v_mov_b32_e32 v9, v244
	s_waitcnt lgkmcnt(0)
	s_barrier
	s_cmpk_gt_i32 s2, 0x6ff
	v_readfirstlane_b32 s3, v9
	s_cbranch_scc1 .LBB0_171
	v_lshlrev_b32_e32 v0, 4, v9
	v_add_u32_e32 v1, 0x2000, v0
	v_ashrrev_i32_e32 v2, 31, v1
	v_lshrrev_b32_e32 v2, 22, v2
	v_add_u32_e32 v2, v1, v2
	v_ashrrev_i32_e32 v8, 10, v2
	v_mul_i32_i24_e32 v2, 0x400, v8
	v_sub_u32_e32 v1, v1, v2
	v_lshrrev_b32_e32 v2, 4, v1
	v_bitop3_b32 v1, v2, v1, 32 bitop3:0x6c
	v_ashrrev_i32_e32 v2, 31, v1
	v_lshrrev_b32_e32 v2, 26, v2
	v_add_u32_e32 v2, v1, v2
	v_lshlrev_b32_e32 v3, 3, v8
	v_ashrrev_i32_e32 v10, 6, v2
	v_and_b32_e32 v3, -16, v3
	v_add_u32_e32 v3, v10, v3
	v_and_b32_e32 v4, 3, v10
	s_mov_b32 s0, 0x1fffe0
	v_lshrrev_b32_e32 v5, 2, v3
	v_lshlrev_b32_e32 v6, 1, v3
	v_and_b32_e32 v2, 0xc0, v2
	v_and_or_b32 v4, v3, s0, v4
	v_and_b32_e32 v5, 4, v5
	v_and_b32_e32 v6, 24, v6
	v_sub_u32_e32 v1, v1, v2
	v_mov_b32_e32 v2, 1
	v_or3_b32 v4, v4, v5, v6
	v_lshlrev_b32_e32 v5, 5, v8
	v_ashrrev_i16_sdwa v1, v2, sext(v1) dst_sel:DWORD dst_unused:UNUSED_PAD src0_sel:DWORD src1_sel:BYTE_0
	v_and_b32_e32 v5, 32, v5
	v_bfe_i32 v11, v1, 0, 16
	v_add_lshl_u32 v1, v5, v11, 1
	v_lshl_add_u32 v128, v4, 11, v1
	v_lshl_add_u32 v130, v3, 11, v1
	v_bfe_i32 v1, v9, 27, 1
	v_lshrrev_b32_e32 v1, 22, v1
	v_add_u32_e32 v1, v0, v1
	v_and_b32_e32 v1, 0xfffffc00, v1
	v_sub_u32_e32 v0, v0, v1
	v_lshrrev_b32_e32 v1, 4, v0
	v_ashrrev_i32_e32 v3, 31, v9
	v_bitop3_b32 v0, v1, v0, 32 bitop3:0x6c
	v_lshrrev_b32_e32 v3, 26, v3
	v_ashrrev_i32_e32 v1, 31, v0
	v_add_u32_e32 v3, v9, v3
	v_lshrrev_b32_e32 v1, 26, v1
	v_ashrrev_i32_e32 v13, 6, v3
	v_add_u32_e32 v1, v0, v1
	v_lshlrev_b32_e32 v3, 3, v13
	v_ashrrev_i32_e32 v12, 6, v1
	v_and_b32_e32 v3, -16, v3
	v_add_u32_e32 v3, v12, v3
	v_and_b32_e32 v4, 3, v12
	s_ashr_i32 s37, s2, 31
	v_and_or_b32 v4, v3, s0, v4
	s_lshr_b32 s0, s37, 29
	s_add_i32 s0, s2, s0
	s_ashr_i32 s4, s3, 6
	s_ashr_i32 s5, s0, 3
	s_and_b32 s0, s0, -8
	s_ashr_i32 s1, s3, 8
	s_lshl_b32 s36, s4, 10
	s_sub_i32 s0, s2, s0
	s_cmp_lt_i32 s0, 0
	s_movk_i32 s38, 0xe1
	s_cselect_b32 s6, s38, 0xe0
	s_mul_i32 s0, s0, s6
	s_add_i32 s0, s0, s5
	s_mul_hi_i32 s5, s0, 0x92492493
	s_add_i32 s5, s5, s0
	s_lshr_b32 s6, s5, 31
	s_ashr_i32 s5, s5, 6
	s_add_i32 s5, s5, s6
	s_lshl_b32 s6, s5, 3
	s_mulk_i32 s5, 0x70
	s_sub_i32 s5, s0, s5
	s_bfe_i32 s0, s5, 0x80000
	s_bfe_u32 s0, s0, 0x3000c
	s_add_i32 s7, s5, s0
	s_bfe_i32 s0, s7, 0x80000
	s_and_b32 s7, s7, 0xf8
	s_sub_i32 s5, s5, s7
	s_sext_i32_i16 s0, s0
	s_sext_i32_i8 s5, s5
	v_lshrrev_b32_e32 v5, 2, v3
	v_lshlrev_b32_e32 v6, 1, v3
	v_and_b32_e32 v1, 0xc0, v1
	s_lshr_b32 s0, s0, 3
	s_add_i32 s14, s6, s5
	v_and_b32_e32 v5, 4, v5
	v_and_b32_e32 v6, 24, v6
	v_sub_u32_e32 v0, v0, v1
	s_ashr_i32 s15, s14, 31
	s_bfe_i64 s[8:9], s[0:1], 0x100000
	v_or3_b32 v4, v4, v5, v6
	v_lshlrev_b32_e32 v5, 5, v13
	v_ashrrev_i16_sdwa v0, v2, sext(v0) dst_sel:DWORD dst_unused:UNUSED_PAD src0_sel:DWORD src1_sel:BYTE_0
	s_lshl_b64 s[6:7], s[14:15], 19
	s_lshl_b64 s[8:9], s[8:9], 19
	v_and_b32_e32 v5, 32, v5
	v_bfe_i32 v14, v0, 0, 16
	s_add_u32 s24, s58, s8
	v_add_lshl_u32 v0, v5, v14, 1
	s_addc_u32 s25, s59, s9
	s_add_i32 s15, s36, 0
	v_lshl_add_u32 v132, v4, 11, v0
	s_add_i32 m0, s15, 0x10000
	v_lshl_add_u32 v134, v3, 11, v0
	global_load_lds_dwordx4 v132, s[24:25]
	s_add_i32 m0, s15, 0x12000
	s_add_u32 s20, s44, s6
	global_load_lds_dwordx4 v128, s[24:25]
	s_addc_u32 s21, s45, s7
	s_mov_b32 m0, s15
	s_add_i32 s39, s15, 0x2000
	global_load_lds_dwordx4 v134, s[20:21]
	s_mov_b32 m0, s39
	s_add_u32 s6, s24, 0x40000
	global_load_lds_dwordx4 v130, s[20:21]
	s_addc_u32 s7, s25, 0
	s_add_i32 m0, s15, 0x14000
	v_mov_b32_e32 v133, 0
	global_load_lds_dwordx4 v132, s[6:7]
	s_add_i32 m0, s15, 0x16000
	v_mov_b32_e32 v129, v133
	global_load_lds_dwordx4 v128, s[6:7]
	s_add_u32 s6, s20, 0x40000
	s_addc_u32 s7, s21, 0
	s_add_i32 s40, s15, 0x4000
	s_mov_b32 m0, s40
	s_add_i32 s41, s15, 0x6000
	global_load_lds_dwordx4 v134, s[6:7]
	s_mov_b32 m0, s41
	v_mov_b32_e32 v135, v133
	global_load_lds_dwordx4 v130, s[6:7]
	v_mov_b32_e32 v131, v133
	s_mov_b32 s42, 0
	v_lshl_add_u64 v[6:7], s[24:25], 0, v[132:133]
	v_lshl_add_u64 v[4:5], s[24:25], 0, v[128:129]
	v_lshl_add_u64 v[2:3], s[20:21], 0, v[134:135]
	s_cmp_lg_u32 s1, 1
	v_lshl_add_u64 v[0:1], s[20:21], 0, v[130:131]
	s_cbranch_scc1 .LBB0_162
	s_barrier

; #define PG8_WAIT_V(n) asm volatile("s_waitcnt vmcnt(" #n ")" ::: "memory")
; #define PG8_BAR __builtin_amdgcn_s_barrier()
; template <class Epi, class Sched>
; __device__ __forceinline__ void gemm_phase(PG8_LAS unsigned char* lds, const Gemm g, const Sched& S, const Epi& E) {
;     ...
;     PG8_WAIT_V(0);
;     if (wr == 0) PG8_BAR;
;     PG8_BAR;
; __device__ __forceinline__ void xcd_barrier(const XcdBarrier& b) {
;     asm volatile("s_waitcnt vmcnt(0)" ::: "memory");
;     __syncthreads();
;     if (threadIdx.x == 0) {
;         unsigned* bar = b.bar;
;         __builtin_amdgcn_s_waitcnt(0);
;         unsigned nloc = b.st[0], nx = b.st[1];
;         if (nloc == 0u) { xcd_barrier_complete(bar, b.x, nloc, nx); b.st[0] = nloc; b.st[1] = nx; }
.LBB0_171:
	s_setprio 0
	s_waitcnt vmcnt(0)
	s_waitcnt vmcnt(0) lgkmcnt(0)
	s_barrier
	s_mov_b64 s[0:1], exec
	v_readlane_b32 s4, v254, 1
	v_readlane_b32 s5, v254, 2
	s_and_b64 s[4:5], s[0:1], s[4:5]
	s_mov_b64 exec, s[4:5]
	s_cbranch_execz .LBB0_223
	s_add_i32 s3, 0, 0x20000
	v_mov_b32_e32 v0, s3
	s_waitcnt vmcnt(0) expcnt(0) lgkmcnt(0)
	ds_read_b32 v2, v0
	s_add_i32 s3, 0, 0x20004
	v_mov_b32_e32 v0, s3
	ds_read_b32 v0, v0
	s_waitcnt lgkmcnt(1)
	v_cmp_ne_u32_e32 vcc, 0, v2
	s_cbranch_vccnz .LBB0_187
	s_add_u32 s4, s58, 0x2f80200
	s_addc_u32 s5, s59, 0
	s_add_u32 s6, s58, 0x2f80400
	s_addc_u32 s7, s59, 0
	s_add_u32 s8, s58, 0x2f80500
	s_addc_u32 s9, s59, 0
	s_add_u32 s10, s58, 0x2f80600
	s_addc_u32 s11, s59, 0
	s_add_u32 s12, s58, 0x2f80700
	s_addc_u32 s13, s59, 0
	s_add_u32 s14, s58, 0x2f80800
	s_addc_u32 s15, s59, 0
	s_add_u32 s20, s58, 0x2f80900
	s_addc_u32 s21, s59, 0
	s_add_u32 s24, s58, 0x2f80a00
	s_addc_u32 s25, s59, 0
	s_add_u32 s26, s58, 0x2f80b00
	s_addc_u32 s27, s59, 0
	s_add_u32 s36, s58, 0x2f80c00
	s_addc_u32 s37, s59, 0
	s_add_u32 s38, s58, 0x2f80d00
	s_addc_u32 s39, s59, 0
	s_add_u32 s40, s58, 0x2f80e00
	s_addc_u32 s41, s59, 0
	s_add_u32 s42, s58, 0x2f80f00
	s_addc_u32 s43, s59, 0
	s_add_u32 s48, s58, 0x2f81000
	s_addc_u32 s49, s59, 0
	s_add_u32 s52, s58, 0x2f81100
	s_addc_u32 s53, s59, 0
	s_add_u32 s60, s58, 0x2f81200
	v_readlane_b32 s3, v254, 0
	s_addc_u32 s61, s59, 0
	s_mul_i32 s3, s97, s3
	s_add_u32 s62, s58, 0x2f81300
	s_mul_i32 s3, s3, s96
	s_addc_u32 s63, s59, 0
	s_mov_b32 s70, 1
	v_mov_b32_e32 v16, 0
	s_branch .LBB0_175

; template <class Epi, class Sched>
; __device__ __forceinline__ void gemm_phase(PG8_LAS unsigned char* lds, const Gemm g, const Sched& S, const Epi& E) {
;     int tid_ = threadIdx.x; asm volatile("" : "+v"(tid_));
;     const int tid = tid_, wid = __builtin_amdgcn_readfirstlane(tid >> 6), lane = tid & 63, wr = wid >> 2, wc = wid & 3, fr = lane & 15, fq = lane >> 4;
;     const int K = g.K, nt = K / BK;
;     unsigned voffA[2], voffB[2];
; #pragma unroll
;     for (int i = 0; i < 2; ++i) { int R, C; stage_rc(tid * 16 + i * 8192, R, C); const int Rb = Epi::PERM ? ((R & ~31) + perm32(R & 31)) : R;
;         voffA[i] = (unsigned)(R * K + C) * 2u; voffB[i] = (unsigned)(Rb * K + C) * 2u; }
;     const size_t kstep = (size_t)(BK * 2);
;     const size_t hstep = (size_t)HALF * K * 2;
;     const size_t tstep = 2 * hstep;
;     const unsigned ldsw = (unsigned)wid * 1024u;
;     const int aoff = lds_byte(wr * 64 + fr, fq * 8), boff = lds_byte(wc * 32 + fr, fq * 8);
;     ...
;     Unit cur, nxt; int ui = 0;
;     if (!S.next(0, cur)) return;
.Lgprio_1:
	v_mov_b32_e32 v8, v244
	s_cmpk_lt_i32 s2, 0x200
	s_waitcnt lgkmcnt(0)
	s_barrier
	s_cselect_b64 s[8:9], -1, 0
	s_cmpk_gt_i32 s2, 0x1ff
	v_readfirstlane_b32 s42, v8
	s_cbranch_scc1 .LBB0_453
	s_ashr_i32 s3, s2, 31
	s_lshr_b32 s0, s3, 29
	s_add_i32 s4, s2, s0
	s_and_b32 s0, s4, -8
	s_sub_i32 s6, s2, s0
	s_cmp_gt_i32 s6, -1
	s_cbranch_scc0 .LBB0_434
	s_lshl_b32 s5, s6, 6
	s_cbranch_execz .LBB0_435
	s_branch .LBB0_436

; #define PG8_WAIT_V(n) asm volatile("s_waitcnt vmcnt(" #n ")" ::: "memory")
; #define PG8_BAR __builtin_amdgcn_s_barrier()
; template <class Epi, class Sched>
; __device__ __forceinline__ void gemm_phase(PG8_LAS unsigned char* lds, const Gemm g, const Sched& S, const Epi& E) {
;     ...
;     PG8_WAIT_V(0);
;     if (wr == 0) PG8_BAR;
;     PG8_BAR;
; __device__ __forceinline__ void xcd_barrier(const XcdBarrier& b) {
;     asm volatile("s_waitcnt vmcnt(0)" ::: "memory");
;     __syncthreads();
;     if (threadIdx.x == 0) {
;         unsigned* bar = b.bar;
;         __builtin_amdgcn_s_waitcnt(0);
;         unsigned nloc = b.st[0], nx = b.st[1];
;         if (nloc == 0u) { xcd_barrier_complete(bar, b.x, nloc, nx); b.st[0] = nloc; b.st[1] = nx; }
.LBB0_475:
	s_setprio 0
	s_waitcnt vmcnt(0)
	s_waitcnt lgkmcnt(0)
	s_barrier
	s_mov_b64 s[0:1], exec
	v_readlane_b32 s4, v254, 1
	v_readlane_b32 s5, v254, 2
	s_and_b64 s[4:5], s[0:1], s[4:5]
	s_mov_b64 exec, s[4:5]
	s_cbranch_execz .LBB0_527
	s_add_i32 s3, 0, 0x20000
	v_mov_b32_e32 v0, s3
	s_waitcnt vmcnt(0) expcnt(0) lgkmcnt(0)
	ds_read_b32 v2, v0
	s_add_i32 s3, 0, 0x20004
	v_mov_b32_e32 v0, s3
	ds_read_b32 v0, v0
	s_waitcnt lgkmcnt(1)
	v_cmp_ne_u32_e32 vcc, 0, v2
	s_cbranch_vccnz .LBB0_491
	s_add_u32 s4, s58, 0x2f80200
	s_addc_u32 s5, s59, 0
	s_add_u32 s6, s58, 0x2f80400
	s_addc_u32 s7, s59, 0
	s_add_u32 s8, s58, 0x2f80500
	s_addc_u32 s9, s59, 0
	s_add_u32 s10, s58, 0x2f80600
	s_addc_u32 s11, s59, 0
	s_add_u32 s12, s58, 0x2f80700
	s_addc_u32 s13, s59, 0
	s_add_u32 s14, s58, 0x2f80800
	s_addc_u32 s15, s59, 0
	s_add_u32 s16, s58, 0x2f80900
	s_addc_u32 s17, s59, 0
	s_add_u32 s18, s58, 0x2f80a00
	s_addc_u32 s19, s59, 0
	s_add_u32 s20, s58, 0x2f80b00
	s_addc_u32 s21, s59, 0
	s_add_u32 s22, s58, 0x2f80c00
	s_addc_u32 s23, s59, 0
	s_add_u32 s24, s58, 0x2f80d00
	s_addc_u32 s25, s59, 0
	s_add_u32 s26, s58, 0x2f80e00
	s_addc_u32 s27, s59, 0
	s_add_u32 s28, s58, 0x2f80f00
	s_addc_u32 s29, s59, 0
	s_add_u32 s30, s58, 0x2f81000
	s_addc_u32 s31, s59, 0
	s_add_u32 s34, s58, 0x2f81100
	s_addc_u32 s35, s59, 0
	s_add_u32 s36, s58, 0x2f81200
	v_readlane_b32 s3, v254, 0
	s_addc_u32 s37, s59, 0
	s_mul_i32 s3, s97, s3
	s_add_u32 s38, s58, 0x2f81300
	s_mul_i32 s3, s3, s96
	s_addc_u32 s39, s59, 0
	s_mov_b32 s64, 1
	v_mov_b32_e32 v16, 0
	s_branch .LBB0_479

; template <class Epi, class Sched>
; __device__ __forceinline__ void gemm_phase(PG8_LAS unsigned char* lds, const Gemm g, const Sched& S, const Epi& E) {
;     int tid_ = threadIdx.x; asm volatile("" : "+v"(tid_));
;     const int tid = tid_, wid = __builtin_amdgcn_readfirstlane(tid >> 6), lane = tid & 63, wr = wid >> 2, wc = wid & 3, fr = lane & 15, fq = lane >> 4;
;     const int K = g.K, nt = K / BK;
;     unsigned voffA[2], voffB[2];
; #pragma unroll
;     for (int i = 0; i < 2; ++i) { int R, C; stage_rc(tid * 16 + i * 8192, R, C); const int Rb = Epi::PERM ? ((R & ~31) + perm32(R & 31)) : R;
;         voffA[i] = (unsigned)(R * K + C) * 2u; voffB[i] = (unsigned)(Rb * K + C) * 2u; }
;     const size_t kstep = (size_t)(BK * 2);
;     const size_t hstep = (size_t)HALF * K * 2;
;     const size_t tstep = 2 * hstep;
;     const unsigned ldsw = (unsigned)wid * 1024u;
;     const int aoff = lds_byte(wr * 64 + fr, fq * 8), boff = lds_byte(wc * 32 + fr, fq * 8);
;     ...
;     Unit cur, nxt; int ui = 0;
;     if (!S.next(0, cur)) return;
.Lgprio_2:
	v_readlane_b32 s0, v254, 37
	v_mov_b32_e32 v8, v244
	v_readlane_b32 s1, v254, 38
	s_waitcnt lgkmcnt(0)
	s_barrier
	s_and_b64 vcc, exec, s[0:1]
	v_readfirstlane_b32 s3, v8
	s_cbranch_vccnz .LBB0_760
	s_ashr_i32 s0, s2, 31
	s_lshr_b32 s0, s0, 29
	s_add_i32 s4, s2, s0
	s_and_b32 s0, s4, -8
	s_sub_i32 s5, s2, s0
	s_cmp_gt_i32 s5, -1
	s_cbranch_scc0 .LBB0_757
	s_lshl_b32 s6, s5, 6
	s_cbranch_execz .LBB0_758
	s_branch .LBB0_759

; #define PG8_WAIT_V(n) asm volatile("s_waitcnt vmcnt(" #n ")" ::: "memory")
; #define PG8_BAR __builtin_amdgcn_s_barrier()
; template <class Epi, class Sched>
; __device__ __forceinline__ void gemm_phase(PG8_LAS unsigned char* lds, const Gemm g, const Sched& S, const Epi& E) {
;     ...
;     PG8_WAIT_V(0);
;     if (wr == 0) PG8_BAR;
;     PG8_BAR;
; __device__ __forceinline__ void xcd_barrier(const XcdBarrier& b) {
;     asm volatile("s_waitcnt vmcnt(0)" ::: "memory");
;     __syncthreads();
;     if (threadIdx.x == 0) {
;         unsigned* bar = b.bar;
;         __builtin_amdgcn_s_waitcnt(0);
;         unsigned nloc = b.st[0], nx = b.st[1];
;         if (nloc == 0u) { xcd_barrier_complete(bar, b.x, nloc, nx); b.st[0] = nloc; b.st[1] = nx; }
.LBB0_792:
	s_setprio 0
	s_waitcnt vmcnt(0)
	s_waitcnt vmcnt(0) lgkmcnt(0)
	s_barrier
	s_mov_b64 s[0:1], exec
	v_readlane_b32 s4, v254, 1
	v_readlane_b32 s5, v254, 2
	s_and_b64 s[4:5], s[0:1], s[4:5]
	s_mov_b64 exec, s[4:5]
	s_cbranch_execz .LBB0_844
	s_add_i32 s3, 0, 0x20000
	v_mov_b32_e32 v0, s3
	s_waitcnt vmcnt(0) expcnt(0) lgkmcnt(0)
	ds_read_b32 v2, v0
	s_add_i32 s3, 0, 0x20004
	v_mov_b32_e32 v0, s3
	ds_read_b32 v0, v0
	s_waitcnt lgkmcnt(1)
	v_cmp_ne_u32_e32 vcc, 0, v2
	s_cbranch_vccnz .LBB0_808
	s_add_u32 s4, s58, 0x2f80200
	s_addc_u32 s5, s59, 0
	s_add_u32 s6, s58, 0x2f80400
	s_addc_u32 s7, s59, 0
	s_add_u32 s8, s58, 0x2f80500
	s_addc_u32 s9, s59, 0
	s_add_u32 s10, s58, 0x2f80600
	s_addc_u32 s11, s59, 0
	s_add_u32 s12, s58, 0x2f80700
	s_addc_u32 s13, s59, 0
	s_add_u32 s14, s58, 0x2f80800
	s_addc_u32 s15, s59, 0
	s_add_u32 s16, s58, 0x2f80900
	s_addc_u32 s17, s59, 0
	s_add_u32 s18, s58, 0x2f80a00
	s_addc_u32 s19, s59, 0
	s_add_u32 s20, s58, 0x2f80b00
	s_addc_u32 s21, s59, 0
	s_add_u32 s22, s58, 0x2f80c00
	s_addc_u32 s23, s59, 0
	s_add_u32 s24, s58, 0x2f80d00
	s_addc_u32 s25, s59, 0
	s_add_u32 s26, s58, 0x2f80e00
	s_addc_u32 s27, s59, 0
	s_add_u32 s28, s58, 0x2f80f00
	s_addc_u32 s29, s59, 0
	s_add_u32 s30, s58, 0x2f81000
	s_addc_u32 s31, s59, 0
	s_add_u32 s34, s58, 0x2f81100
	s_addc_u32 s35, s59, 0
	s_add_u32 s36, s58, 0x2f81200
	v_readlane_b32 s3, v254, 0
	s_addc_u32 s37, s59, 0
	s_mul_i32 s3, s97, s3
	s_add_u32 s38, s58, 0x2f81300
	s_mul_i32 s3, s3, s96
	s_addc_u32 s39, s59, 0
	s_mov_b32 s50, 1
	v_mov_b32_e32 v16, 0
	s_branch .LBB0_796

; #define PG8_STAGE(bufoff, gbase, voff) do { _Pragma("unroll") for (int _i = 0; _i < 2; ++_i) \
;         __builtin_amdgcn_global_load_lds((const unsigned*)((const char*)(gbase) + (voff)[_i]), (PG8_LAS unsigned*)(lds + (bufoff) + ldsw + _i * 8192), 16, 0, 0); } while (0)
; template <class Epi, class Sched>
; __device__ __forceinline__ void gemm_phase(PG8_LAS unsigned char* lds, const Gemm g, const Sched& S, const Epi& E) {
;     ...
;     for (int i = 0; i < 2; ++i) { int R, C; stage_rc(tid * 16 + i * 8192, R, C); const int Rb = Epi::PERM ? ((R & ~31) + perm32(R & 31)) : R;
;         voffA[i] = (unsigned)(R * K + C) * 2u; voffB[i] = (unsigned)(Rb * K + C) * 2u; }
;     const size_t kstep = (size_t)(BK * 2);
;     const size_t hstep = (size_t)HALF * K * 2;
;     const size_t tstep = 2 * hstep;
;     const unsigned ldsw = (unsigned)wid * 1024u;
;     const int aoff = lds_byte(wr * 64 + fr, fq * 8), boff = lds_byte(wc * 32 + fr, fq * 8);
;     ...
;     Unit cur, nxt; int ui = 0;
;     if (!S.next(0, cur)) return;
;     f32x4 acc[2][2][4][2];
; #pragma unroll
;     for (int a = 0; a < 2; ++a)
; #pragma unroll
;         for (int b = 0; b < 2; ++b)
; #pragma unroll
;             for (int m = 0; m < 4; ++m)
; #pragma unroll
;                 for (int n = 0; n < 2; ++n) acc[a][b][m][n] = (f32x4){0.f, 0.f, 0.f, 0.f};
;     bf16x8 At[4][2], B0[2][2], B1[2][2];
;     const char* cA = (const char*)g.A + (size_t)cur.pm * tstep; const char* cB = (const char*)g.Bt + (size_t)cur.pn * tstep;
;     S.a_ready(cur);
;     PG8_STAGE(PG8_SB(0, 0), cB, voffB); PG8_STAGE(PG8_SA(0, 0), cA, voffA); PG8_STAGE(PG8_SB(0, 1), cB + hstep, voffB); PG8_STAGE(PG8_SA(0, 1), cA + hstep, voffA);
.Lgprio_3:
	v_mov_b32_e32 v9, v244
	s_waitcnt lgkmcnt(0)
	s_barrier
	s_cmpk_gt_i32 s2, 0xaff
	v_readfirstlane_b32 s3, v9
	s_cbranch_scc1 .LBB0_911
	v_lshlrev_b32_e32 v0, 4, v9
	v_add_u32_e32 v1, 0x2000, v0
	v_ashrrev_i32_e32 v2, 31, v1
	v_lshrrev_b32_e32 v2, 22, v2
	v_add_u32_e32 v2, v1, v2
	v_ashrrev_i32_e32 v8, 10, v2
	v_mul_i32_i24_e32 v2, 0x400, v8
	v_sub_u32_e32 v1, v1, v2
	v_lshrrev_b32_e32 v2, 4, v1
	v_bitop3_b32 v1, v2, v1, 32 bitop3:0x6c
	v_ashrrev_i32_e32 v2, 31, v1
	v_lshrrev_b32_e32 v2, 26, v2
	v_add_u32_e32 v2, v1, v2
	v_lshlrev_b32_e32 v3, 3, v8
	v_ashrrev_i32_e32 v10, 6, v2
	v_and_b32_e32 v3, -16, v3
	v_add_u32_e32 v3, v10, v3
	v_and_b32_e32 v4, 3, v10
	s_mov_b32 s0, 0x1fffe0
	v_lshrrev_b32_e32 v5, 2, v3
	v_lshlrev_b32_e32 v6, 1, v3
	v_and_b32_e32 v2, 0xc0, v2
	v_and_or_b32 v4, v3, s0, v4
	v_and_b32_e32 v5, 4, v5
	v_and_b32_e32 v6, 24, v6
	v_sub_u32_e32 v1, v1, v2
	v_mov_b32_e32 v2, 1
	v_or3_b32 v4, v4, v5, v6
	v_lshlrev_b32_e32 v5, 5, v8
	v_ashrrev_i16_sdwa v1, v2, sext(v1) dst_sel:DWORD dst_unused:UNUSED_PAD src0_sel:DWORD src1_sel:BYTE_0
	v_and_b32_e32 v5, 32, v5
	v_bfe_i32 v11, v1, 0, 16
	v_add_lshl_u32 v1, v5, v11, 1
	v_lshl_add_u32 v128, v4, 11, v1
	v_lshl_add_u32 v130, v3, 11, v1
	v_bfe_i32 v1, v9, 27, 1
	v_lshrrev_b32_e32 v1, 22, v1
	v_add_u32_e32 v1, v0, v1
	v_and_b32_e32 v1, 0xfffffc00, v1
	v_sub_u32_e32 v0, v0, v1
	v_lshrrev_b32_e32 v1, 4, v0
	v_ashrrev_i32_e32 v3, 31, v9
	v_bitop3_b32 v0, v1, v0, 32 bitop3:0x6c
	v_lshrrev_b32_e32 v3, 26, v3
	v_ashrrev_i32_e32 v1, 31, v0
	v_add_u32_e32 v3, v9, v3
	v_lshrrev_b32_e32 v1, 26, v1
	v_ashrrev_i32_e32 v13, 6, v3
	v_add_u32_e32 v1, v0, v1
	v_lshlrev_b32_e32 v3, 3, v13
	s_add_u32 s22, s58, 0xb00000
	v_ashrrev_i32_e32 v12, 6, v1
	v_and_b32_e32 v3, -16, v3
	s_addc_u32 s23, s59, 0
	v_add_u32_e32 v3, v12, v3
	v_and_b32_e32 v4, 3, v12
	s_ashr_i32 s25, s2, 31
	v_and_or_b32 v4, v3, s0, v4
	s_lshr_b32 s0, s25, 29
	s_add_i32 s0, s2, s0
	s_ashr_i32 s4, s3, 6
	s_ashr_i32 s5, s0, 3
	s_and_b32 s0, s0, -8
	s_ashr_i32 s1, s3, 8
	s_lshl_b32 s24, s4, 10
	s_sub_i32 s0, s2, s0
	s_cmp_lt_i32 s0, 0
	s_movk_i32 s26, 0x161
	s_cselect_b32 s6, s26, 0x160
	s_mul_i32 s0, s0, s6
	s_add_i32 s0, s0, s5
	s_mul_hi_i32 s5, s0, 0x2e8ba2e9
	s_lshr_b32 s6, s5, 31
	s_ashr_i32 s5, s5, 5
	s_add_i32 s5, s5, s6
	s_lshl_b32 s6, s5, 3
	s_mulk_i32 s5, 0xb0
	s_sub_i32 s5, s0, s5
	s_sext_i32_i16 s0, s5
	s_bfe_u32 s0, s0, 0x3001c
	s_add_i32 s7, s5, s0
	s_sext_i32_i16 s0, s7
	s_and_b32 s7, s7, 0xfff8
	s_sub_i32 s5, s5, s7
	s_sext_i32_i16 s5, s5
	v_lshrrev_b32_e32 v5, 2, v3
	v_lshlrev_b32_e32 v6, 1, v3
	v_and_b32_e32 v1, 0xc0, v1
	s_lshr_b32 s0, s0, 3
	s_add_i32 s14, s6, s5
	v_and_b32_e32 v5, 4, v5
	v_and_b32_e32 v6, 24, v6
	v_sub_u32_e32 v0, v0, v1
	s_ashr_i32 s15, s14, 31
	s_bfe_i64 s[8:9], s[0:1], 0x100000
	v_or3_b32 v4, v4, v5, v6
	v_lshlrev_b32_e32 v5, 5, v13
	v_ashrrev_i16_sdwa v0, v2, sext(v0) dst_sel:DWORD dst_unused:UNUSED_PAD src0_sel:DWORD src1_sel:BYTE_0
	s_lshl_b64 s[6:7], s[14:15], 19
	s_lshl_b64 s[8:9], s[8:9], 19
	v_and_b32_e32 v5, 32, v5
	v_bfe_i32 v14, v0, 0, 16
	s_add_u32 s18, s22, s8
	v_add_lshl_u32 v0, v5, v14, 1
	s_addc_u32 s19, s23, s9
	s_add_i32 s15, s24, 0
	v_lshl_add_u32 v132, v4, 11, v0
	s_add_i32 m0, s15, 0x10000
	v_lshl_add_u32 v134, v3, 11, v0
	global_load_lds_dwordx4 v132, s[18:19]
	s_add_i32 m0, s15, 0x12000
	s_add_u32 s16, s44, s6
	global_load_lds_dwordx4 v128, s[18:19]
	s_addc_u32 s17, s45, s7
	s_mov_b32 m0, s15
	s_add_i32 s27, s15, 0x2000
	global_load_lds_dwordx4 v134, s[16:17]
	s_mov_b32 m0, s27
	s_add_u32 s6, s18, 0x40000
	global_load_lds_dwordx4 v130, s[16:17]
	s_addc_u32 s7, s19, 0
	s_add_i32 m0, s15, 0x14000
	v_mov_b32_e32 v133, 0
	global_load_lds_dwordx4 v132, s[6:7]
	s_add_i32 m0, s15, 0x16000
	v_mov_b32_e32 v129, v133
	global_load_lds_dwordx4 v128, s[6:7]
	s_add_u32 s6, s16, 0x40000
	s_addc_u32 s7, s17, 0
	s_add_i32 s28, s15, 0x4000
	s_mov_b32 m0, s28
	s_add_i32 s29, s15, 0x6000
	global_load_lds_dwordx4 v134, s[6:7]
	s_mov_b32 m0, s29
	v_mov_b32_e32 v135, v133
	global_load_lds_dwordx4 v130, s[6:7]
	v_mov_b32_e32 v131, v133
	s_mov_b32 s30, 0
	v_lshl_add_u64 v[6:7], s[18:19], 0, v[132:133]
	v_lshl_add_u64 v[4:5], s[18:19], 0, v[128:129]
	v_lshl_add_u64 v[2:3], s[16:17], 0, v[134:135]
	s_cmp_lg_u32 s1, 1
	v_lshl_add_u64 v[0:1], s[16:17], 0, v[130:131]
	s_cbranch_scc1 .LBB0_902
	s_barrier

; #define PG8_WAIT_V(n) asm volatile("s_waitcnt vmcnt(" #n ")" ::: "memory")
; #define PG8_BAR __builtin_amdgcn_s_barrier()
; template <class Epi, class Sched>
; __device__ __forceinline__ void gemm_phase(PG8_LAS unsigned char* lds, const Gemm g, const Sched& S, const Epi& E) {
;     ...
;     PG8_WAIT_V(0);
;     if (wr == 0) PG8_BAR;
;     PG8_BAR;
; __device__ __forceinline__ void xcd_barrier(const XcdBarrier& b) {
;     asm volatile("s_waitcnt vmcnt(0)" ::: "memory");
;     __syncthreads();
;     if (threadIdx.x == 0) {
;         unsigned* bar = b.bar;
;         __builtin_amdgcn_s_waitcnt(0);
;         unsigned nloc = b.st[0], nx = b.st[1];
;         if (nloc == 0u) { xcd_barrier_complete(bar, b.x, nloc, nx); b.st[0] = nloc; b.st[1] = nx; }
.LBB0_1025:
	s_setprio 0
	s_waitcnt vmcnt(0)
	s_waitcnt vmcnt(0) lgkmcnt(0)
	s_barrier
	s_mov_b64 s[0:1], exec
	v_readlane_b32 s4, v254, 1
	v_readlane_b32 s5, v254, 2
	s_and_b64 s[4:5], s[0:1], s[4:5]
	s_mov_b64 exec, s[4:5]
	s_cbranch_execz .LBB0_1077
	s_add_i32 s3, 0, 0x20000
	v_mov_b32_e32 v0, s3
	s_waitcnt vmcnt(0) expcnt(0) lgkmcnt(0)
	ds_read_b32 v2, v0
	s_add_i32 s3, 0, 0x20004
	v_mov_b32_e32 v0, s3
	ds_read_b32 v0, v0
	s_waitcnt lgkmcnt(1)
	v_cmp_ne_u32_e32 vcc, 0, v2
	s_cbranch_vccnz .LBB0_1041
	s_add_u32 s4, s58, 0x2f80200
	s_addc_u32 s5, s59, 0
	s_add_u32 s6, s58, 0x2f80400
	s_addc_u32 s7, s59, 0
	s_add_u32 s10, s58, 0x2f80500
	s_addc_u32 s11, s59, 0
	s_add_u32 s12, s58, 0x2f80600
	s_addc_u32 s13, s59, 0
	s_add_u32 s14, s58, 0x2f80700
	s_addc_u32 s15, s59, 0
	s_add_u32 s16, s58, 0x2f80800
	s_addc_u32 s17, s59, 0
	s_add_u32 s18, s58, 0x2f80900
	s_addc_u32 s19, s59, 0
	s_add_u32 s20, s58, 0x2f80a00
	s_addc_u32 s21, s59, 0
	s_add_u32 s22, s58, 0x2f80b00
	s_addc_u32 s23, s59, 0
	s_add_u32 s24, s58, 0x2f80c00
	s_addc_u32 s25, s59, 0
	s_add_u32 s26, s58, 0x2f80d00
	s_addc_u32 s27, s59, 0
	s_add_u32 s28, s58, 0x2f80e00
	s_addc_u32 s29, s59, 0
	s_add_u32 s30, s58, 0x2f80f00
	s_addc_u32 s31, s59, 0
	s_add_u32 s34, s58, 0x2f81000
	s_addc_u32 s35, s59, 0
	s_add_u32 s36, s58, 0x2f81100
	s_addc_u32 s37, s59, 0
	s_add_u32 s38, s58, 0x2f81200
	v_readlane_b32 s3, v254, 0
	s_addc_u32 s39, s59, 0
	s_mul_i32 s3, s97, s3
	s_add_u32 s40, s58, 0x2f81300
	s_mul_i32 s3, s3, s96
	s_addc_u32 s41, s59, 0
	s_mov_b32 s52, 1
	v_mov_b32_e32 v16, 0
	s_branch .LBB0_1029

; template <class Epi, class Sched>
; __device__ __forceinline__ void gemm_phase(PG8_LAS unsigned char* lds, const Gemm g, const Sched& S, const Epi& E) {
;     int tid_ = threadIdx.x; asm volatile("" : "+v"(tid_));
;     const int tid = tid_, wid = __builtin_amdgcn_readfirstlane(tid >> 6), lane = tid & 63, wr = wid >> 2, wc = wid & 3, fr = lane & 15, fq = lane >> 4;
;     const int K = g.K, nt = K / BK;
;     unsigned voffA[2], voffB[2];
; #pragma unroll
;     for (int i = 0; i < 2; ++i) { int R, C; stage_rc(tid * 16 + i * 8192, R, C); const int Rb = Epi::PERM ? ((R & ~31) + perm32(R & 31)) : R;
;         voffA[i] = (unsigned)(R * K + C) * 2u; voffB[i] = (unsigned)(Rb * K + C) * 2u; }
;     const size_t kstep = (size_t)(BK * 2);
;     const size_t hstep = (size_t)HALF * K * 2;
;     const size_t tstep = 2 * hstep;
;     const unsigned ldsw = (unsigned)wid * 1024u;
;     const int aoff = lds_byte(wr * 64 + fr, fq * 8), boff = lds_byte(wc * 32 + fr, fq * 8);
;     ...
;     Unit cur, nxt; int ui = 0;
;     if (!S.next(0, cur)) return;
.Lgprio_5:
	v_readlane_b32 s0, v254, 37
	v_mov_b32_e32 v8, v244
	v_readlane_b32 s1, v254, 38
	s_waitcnt lgkmcnt(0)
	s_barrier
	s_and_b64 vcc, exec, s[0:1]
	v_readfirstlane_b32 s3, v8
	s_cbranch_vccnz .LBB0_1138
	s_ashr_i32 s0, s2, 31
	s_lshr_b32 s0, s0, 29
	s_add_i32 s6, s2, s0
	s_and_b32 s0, s6, -8
	s_sub_i32 s4, s2, s0
	s_cmp_gt_i32 s4, -1
	s_cbranch_scc0 .LBB0_1135
	s_lshl_b32 s5, s4, 6
	s_ashr_i32 s0, s6, 3
	s_cbranch_execz .LBB0_1136
	s_branch .LBB0_1137

; #define PG8_WAIT_V(n) asm volatile("s_waitcnt vmcnt(" #n ")" ::: "memory")
; #define PG8_BAR __builtin_amdgcn_s_barrier()
; template <class Epi, class Sched>
; __device__ __forceinline__ void gemm_phase(PG8_LAS unsigned char* lds, const Gemm g, const Sched& S, const Epi& E) {
;     ...
;     PG8_WAIT_V(0);
;     if (wr == 0) PG8_BAR;
;     PG8_BAR;
; __device__ __forceinline__ void xcd_barrier(const XcdBarrier& b) {
;     asm volatile("s_waitcnt vmcnt(0)" ::: "memory");
;     __syncthreads();
;     if (threadIdx.x == 0) {
;         unsigned* bar = b.bar;
;         __builtin_amdgcn_s_waitcnt(0);
;         unsigned nloc = b.st[0], nx = b.st[1];
;         if (nloc == 0u) { xcd_barrier_complete(bar, b.x, nloc, nx); b.st[0] = nloc; b.st[1] = nx; }
.LBB0_1170:
	s_setprio 0
	s_waitcnt vmcnt(0)
	s_waitcnt lgkmcnt(0)
	s_barrier
	s_mov_b64 s[0:1], exec
	v_readlane_b32 s2, v254, 1
	v_readlane_b32 s3, v254, 2
	s_and_b64 s[2:3], s[0:1], s[2:3]
	s_mov_b64 exec, s[2:3]
	s_cbranch_execz .LBB0_1222
	s_add_i32 s2, 0, 0x20000
	v_mov_b32_e32 v0, s2
	s_waitcnt vmcnt(0) expcnt(0) lgkmcnt(0)
	ds_read_b32 v2, v0
	s_add_i32 s2, 0, 0x20004
	v_mov_b32_e32 v0, s2
	ds_read_b32 v0, v0
	s_waitcnt lgkmcnt(1)
	v_cmp_ne_u32_e32 vcc, 0, v2
	s_cbranch_vccnz .LBB0_1186
	v_readlane_b32 s2, v254, 0
	s_mul_i32 s44, s97, s2
	s_add_u32 s2, s58, 0x2f80200
	s_addc_u32 s3, s59, 0
	s_add_u32 s4, s58, 0x2f80400
	s_addc_u32 s5, s59, 0
	s_add_u32 s6, s58, 0x2f80500
	s_addc_u32 s7, s59, 0
	s_add_u32 s8, s58, 0x2f80600
	s_addc_u32 s9, s59, 0
	s_add_u32 s10, s58, 0x2f80700
	s_addc_u32 s11, s59, 0
	s_add_u32 s12, s58, 0x2f80800
	s_addc_u32 s13, s59, 0
	s_add_u32 s14, s58, 0x2f80900
	s_addc_u32 s15, s59, 0
	s_add_u32 s16, s58, 0x2f80a00
	s_addc_u32 s17, s59, 0
	s_add_u32 s18, s58, 0x2f80b00
	s_addc_u32 s19, s59, 0
	s_add_u32 s20, s58, 0x2f80c00
	s_addc_u32 s21, s59, 0
	s_add_u32 s22, s58, 0x2f80d00
	s_addc_u32 s23, s59, 0
	s_add_u32 s24, s58, 0x2f80e00
	s_addc_u32 s25, s59, 0
	s_add_u32 s26, s58, 0x2f80f00
	s_addc_u32 s27, s59, 0
	s_add_u32 s28, s58, 0x2f81000
	s_addc_u32 s29, s59, 0
	s_add_u32 s30, s58, 0x2f81100
	s_addc_u32 s31, s59, 0
	s_add_u32 s34, s58, 0x2f81200
	s_addc_u32 s35, s59, 0
	s_add_u32 s36, s58, 0x2f81300
	s_mul_i32 s44, s44, s96
	s_addc_u32 s37, s59, 0
	s_mov_b32 s45, 1
	v_mov_b32_e32 v16, 0
	s_branch .LBB0_1174
